# v36 + gla_scan chunk-state recurrence fully unrolled with kv/decay loads prefetched 16 chunks ahead (was 64 dependent load round trips)
# speedup vs baseline: 1.0143x; 1.0036x over previous
; __device__ __forceinline__ unsigned pk2(float lo, float hi) { const f32v2_t v = {lo, hi}; const bf16v2_t b = __builtin_convertvector(v, bf16v2_t); return __builtin_bit_cast(unsigned, b); }
; __device__ __forceinline__ float bflo(unsigned w) { return __uint_as_float(w << 16); }
; __device__ __forceinline__ float bfhi(unsigned w) { return __uint_as_float(w & 0xffff0000u); }
; __device__ __forceinline__ int otid() { int t = threadIdx.x; asm volatile("" : "+v"(t)); return t; }
; __device__ __forceinline__ void gla_scan(const Args& a, int G, size_t dst_off = WS_KV) {
;     ...
;     for (int id = blockIdx.x * 512 + otid(); id < 16 * 256 * 32; id += G * 512) {
;         const int bh = id >> 13, v = (id >> 5) & 255, d0 = (id & 31) * 4;
;         float s0 = 0.f, s1 = 0.f, s2 = 0.f, s3 = 0.f;
; #pragma unroll 8
;         for (int n = 0; n < 64; ++n) {
;             const int unit = bh * 64 + n;
;             u32x2* p = (u32x2*)(KV + ((size_t)unit * 256 + v) * 128 + d0);
;             const u32x2 kv = *p; const f32x4 dc = *(const f32x4*)(DEC + (size_t)unit * 128 + d0);
;             u32x2 o; o.x = pk2(s0, s1); o.y = pk2(s2, s3); *(u32x2*)((char*)p + dd) = o;
;             s0 = dc[0] * s0 + bflo(kv.x); s1 = dc[1] * s1 + bfhi(kv.x); s2 = dc[2] * s2 + bflo(kv.y); s3 = dc[3] * s3 + bfhi(kv.y);
;         }
.LBB0_324:
	s_mov_b32 s101, 0
	v_lshl_add_u64 v[24:25], s[82:83], 0, v[2:3]
	s_mov_b32 s100, 0x1a800000
	v_lshl_add_u64 v[24:25], v[24:25], 0, s[100:101]
	v_lshl_add_u64 v[26:27], s[82:83], 0, v[0:1]
	s_mov_b32 s100, 0x300000
	v_lshl_add_u64 v[26:27], v[26:27], 0, s[100:101]
	s_mov_b32 s100, 0x0
	v_lshl_add_u64 v[28:29], v[24:25], 0, s[100:101]
	global_load_dwordx2 v[32:33], v[28:29], off
	s_mov_b32 s100, 0x0
	v_lshl_add_u64 v[28:29], v[26:27], 0, s[100:101]
	global_load_dwordx4 v[34:37], v[28:29], off
	s_mov_b32 s100, 0x10000
	v_lshl_add_u64 v[28:29], v[24:25], 0, s[100:101]
	global_load_dwordx2 v[38:39], v[28:29], off
	s_mov_b32 s100, 0x200
	v_lshl_add_u64 v[28:29], v[26:27], 0, s[100:101]
	global_load_dwordx4 v[40:43], v[28:29], off
	s_mov_b32 s100, 0x20000
	v_lshl_add_u64 v[28:29], v[24:25], 0, s[100:101]
	global_load_dwordx2 v[44:45], v[28:29], off
	s_mov_b32 s100, 0x400
	v_lshl_add_u64 v[28:29], v[26:27], 0, s[100:101]
	global_load_dwordx4 v[46:49], v[28:29], off
	s_mov_b32 s100, 0x30000
	v_lshl_add_u64 v[28:29], v[24:25], 0, s[100:101]
	global_load_dwordx2 v[50:51], v[28:29], off
	s_mov_b32 s100, 0x600
	v_lshl_add_u64 v[28:29], v[26:27], 0, s[100:101]
	global_load_dwordx4 v[52:55], v[28:29], off
	s_mov_b32 s100, 0x40000
	v_lshl_add_u64 v[28:29], v[24:25], 0, s[100:101]
	global_load_dwordx2 v[56:57], v[28:29], off
	s_mov_b32 s100, 0x800
	v_lshl_add_u64 v[28:29], v[26:27], 0, s[100:101]
	global_load_dwordx4 v[58:61], v[28:29], off
	s_mov_b32 s100, 0x50000
	v_lshl_add_u64 v[28:29], v[24:25], 0, s[100:101]
	global_load_dwordx2 v[62:63], v[28:29], off
	s_mov_b32 s100, 0xa00
	v_lshl_add_u64 v[28:29], v[26:27], 0, s[100:101]
	global_load_dwordx4 v[64:67], v[28:29], off
	s_mov_b32 s100, 0x60000
	v_lshl_add_u64 v[28:29], v[24:25], 0, s[100:101]
	global_load_dwordx2 v[68:69], v[28:29], off
	s_mov_b32 s100, 0xc00
	v_lshl_add_u64 v[28:29], v[26:27], 0, s[100:101]
	global_load_dwordx4 v[70:73], v[28:29], off
	s_mov_b32 s100, 0x70000
	v_lshl_add_u64 v[28:29], v[24:25], 0, s[100:101]
	global_load_dwordx2 v[74:75], v[28:29], off
	s_mov_b32 s100, 0xe00
	v_lshl_add_u64 v[28:29], v[26:27], 0, s[100:101]
	global_load_dwordx4 v[76:79], v[28:29], off
	s_mov_b32 s100, 0x80000
	v_lshl_add_u64 v[28:29], v[24:25], 0, s[100:101]
	global_load_dwordx2 v[80:81], v[28:29], off
	s_mov_b32 s100, 0x1000
	v_lshl_add_u64 v[28:29], v[26:27], 0, s[100:101]
	global_load_dwordx4 v[82:85], v[28:29], off
	s_mov_b32 s100, 0x90000
	v_lshl_add_u64 v[28:29], v[24:25], 0, s[100:101]
	global_load_dwordx2 v[86:87], v[28:29], off
	s_mov_b32 s100, 0x1200
	v_lshl_add_u64 v[28:29], v[26:27], 0, s[100:101]
	global_load_dwordx4 v[88:91], v[28:29], off
	s_mov_b32 s100, 0xa0000
	v_lshl_add_u64 v[28:29], v[24:25], 0, s[100:101]
	global_load_dwordx2 v[92:93], v[28:29], off
	s_mov_b32 s100, 0x1400
	v_lshl_add_u64 v[28:29], v[26:27], 0, s[100:101]
	global_load_dwordx4 v[94:97], v[28:29], off
	s_mov_b32 s100, 0xb0000
	v_lshl_add_u64 v[28:29], v[24:25], 0, s[100:101]
	global_load_dwordx2 v[98:99], v[28:29], off
	s_mov_b32 s100, 0x1600
	v_lshl_add_u64 v[28:29], v[26:27], 0, s[100:101]
	global_load_dwordx4 v[100:103], v[28:29], off
	s_mov_b32 s100, 0xc0000
	v_lshl_add_u64 v[28:29], v[24:25], 0, s[100:101]
	global_load_dwordx2 v[104:105], v[28:29], off
	s_mov_b32 s100, 0x1800
	v_lshl_add_u64 v[28:29], v[26:27], 0, s[100:101]
	global_load_dwordx4 v[106:109], v[28:29], off
	s_mov_b32 s100, 0xd0000
	v_lshl_add_u64 v[28:29], v[24:25], 0, s[100:101]
	global_load_dwordx2 v[110:111], v[28:29], off
	s_mov_b32 s100, 0x1a00
	v_lshl_add_u64 v[28:29], v[26:27], 0, s[100:101]
	global_load_dwordx4 v[112:115], v[28:29], off
	s_mov_b32 s100, 0xe0000
	v_lshl_add_u64 v[28:29], v[24:25], 0, s[100:101]
	global_load_dwordx2 v[116:117], v[28:29], off
	s_mov_b32 s100, 0x1c00
	v_lshl_add_u64 v[28:29], v[26:27], 0, s[100:101]
	global_load_dwordx4 v[118:121], v[28:29], off
	s_mov_b32 s100, 0xf0000
	v_lshl_add_u64 v[28:29], v[24:25], 0, s[100:101]
	global_load_dwordx2 v[122:123], v[28:29], off
	s_mov_b32 s100, 0x1e00
	v_lshl_add_u64 v[28:29], v[26:27], 0, s[100:101]
	global_load_dwordx4 v[124:127], v[28:29], off
	v_cvt_pk_bf16_f32 v22, v8, v9
	v_cvt_pk_bf16_f32 v23, v10, v11
	s_mov_b32 s100, 0x0
	v_lshl_add_u64 v[30:31], v[24:25], 0, s[100:101]
	global_store_dwordx2 v[30:31], v[22:23], off
	s_waitcnt vmcnt(31)
	v_lshlrev_b32_e32 v18, 16, v32
	v_and_b32_e32 v19, 0xffff0000, v32
	v_lshlrev_b32_e32 v20, 16, v33
	v_and_b32_e32 v21, 0xffff0000, v33
	v_pk_fma_f32 v[8:9], v[8:9], v[34:35], v[18:19]
	v_pk_fma_f32 v[10:11], v[10:11], v[36:37], v[20:21]
	s_mov_b32 s100, 0x100000
	v_lshl_add_u64 v[28:29], v[24:25], 0, s[100:101]
	global_load_dwordx2 v[32:33], v[28:29], off
	s_mov_b32 s100, 0x2000
	v_lshl_add_u64 v[28:29], v[26:27], 0, s[100:101]
	global_load_dwordx4 v[34:37], v[28:29], off
	v_cvt_pk_bf16_f32 v22, v8, v9
	v_cvt_pk_bf16_f32 v23, v10, v11
	s_mov_b32 s100, 0x10000
	v_lshl_add_u64 v[30:31], v[24:25], 0, s[100:101]
	global_store_dwordx2 v[30:31], v[22:23], off
	s_waitcnt vmcnt(32)
	v_lshlrev_b32_e32 v18, 16, v38
	v_and_b32_e32 v19, 0xffff0000, v38
	v_lshlrev_b32_e32 v20, 16, v39
	v_and_b32_e32 v21, 0xffff0000, v39
	v_pk_fma_f32 v[8:9], v[8:9], v[40:41], v[18:19]
	v_pk_fma_f32 v[10:11], v[10:11], v[42:43], v[20:21]
	s_mov_b32 s100, 0x110000
	v_lshl_add_u64 v[28:29], v[24:25], 0, s[100:101]
	global_load_dwordx2 v[38:39], v[28:29], off
	s_mov_b32 s100, 0x2200
	v_lshl_add_u64 v[28:29], v[26:27], 0, s[100:101]
	global_load_dwordx4 v[40:43], v[28:29], off
	v_cvt_pk_bf16_f32 v22, v8, v9
	v_cvt_pk_bf16_f32 v23, v10, v11
	s_mov_b32 s100, 0x20000
	v_lshl_add_u64 v[30:31], v[24:25], 0, s[100:101]
	global_store_dwordx2 v[30:31], v[22:23], off
	s_waitcnt vmcnt(33)
; __device__ __forceinline__ unsigned pk2(float lo, float hi) { const f32v2_t v = {lo, hi}; const bf16v2_t b = __builtin_convertvector(v, bf16v2_t); return __builtin_bit_cast(unsigned, b); }
; __device__ __forceinline__ float bflo(unsigned w) { return __uint_as_float(w << 16); }
; __device__ __forceinline__ float bfhi(unsigned w) { return __uint_as_float(w & 0xffff0000u); }
; __device__ __forceinline__ int otid() { int t = threadIdx.x; asm volatile("" : "+v"(t)); return t; }
; __device__ __forceinline__ void gla_scan(const Args& a, int G, size_t dst_off = WS_KV) {
;     ...
;     for (int id = blockIdx.x * 512 + otid(); id < 16 * 256 * 32; id += G * 512) {
;         const int bh = id >> 13, v = (id >> 5) & 255, d0 = (id & 31) * 4;
;         float s0 = 0.f, s1 = 0.f, s2 = 0.f, s3 = 0.f;
; #pragma unroll 8
;         for (int n = 0; n < 64; ++n) {
;             const int unit = bh * 64 + n;
;             u32x2* p = (u32x2*)(KV + ((size_t)unit * 256 + v) * 128 + d0);
;             const u32x2 kv = *p; const f32x4 dc = *(const f32x4*)(DEC + (size_t)unit * 128 + d0);
;             u32x2 o; o.x = pk2(s0, s1); o.y = pk2(s2, s3); *(u32x2*)((char*)p + dd) = o;
;             s0 = dc[0] * s0 + bflo(kv.x); s1 = dc[1] * s1 + bfhi(kv.x); s2 = dc[2] * s2 + bflo(kv.y); s3 = dc[3] * s3 + bfhi(kv.y);
;         }
	v_lshlrev_b32_e32 v18, 16, v44
	v_and_b32_e32 v19, 0xffff0000, v44
	v_lshlrev_b32_e32 v20, 16, v45
	v_and_b32_e32 v21, 0xffff0000, v45
	v_pk_fma_f32 v[8:9], v[8:9], v[46:47], v[18:19]
	v_pk_fma_f32 v[10:11], v[10:11], v[48:49], v[20:21]
	s_mov_b32 s100, 0x120000
	v_lshl_add_u64 v[28:29], v[24:25], 0, s[100:101]
	global_load_dwordx2 v[44:45], v[28:29], off
	s_mov_b32 s100, 0x2400
	v_lshl_add_u64 v[28:29], v[26:27], 0, s[100:101]
	global_load_dwordx4 v[46:49], v[28:29], off
	v_cvt_pk_bf16_f32 v22, v8, v9
	v_cvt_pk_bf16_f32 v23, v10, v11
	s_mov_b32 s100, 0x30000
	v_lshl_add_u64 v[30:31], v[24:25], 0, s[100:101]
	global_store_dwordx2 v[30:31], v[22:23], off
	s_waitcnt vmcnt(34)
	v_lshlrev_b32_e32 v18, 16, v50
	v_and_b32_e32 v19, 0xffff0000, v50
	v_lshlrev_b32_e32 v20, 16, v51
	v_and_b32_e32 v21, 0xffff0000, v51
	v_pk_fma_f32 v[8:9], v[8:9], v[52:53], v[18:19]
	v_pk_fma_f32 v[10:11], v[10:11], v[54:55], v[20:21]
	s_mov_b32 s100, 0x130000
	v_lshl_add_u64 v[28:29], v[24:25], 0, s[100:101]
	global_load_dwordx2 v[50:51], v[28:29], off
	s_mov_b32 s100, 0x2600
	v_lshl_add_u64 v[28:29], v[26:27], 0, s[100:101]
	global_load_dwordx4 v[52:55], v[28:29], off
	v_cvt_pk_bf16_f32 v22, v8, v9
	v_cvt_pk_bf16_f32 v23, v10, v11
	s_mov_b32 s100, 0x40000
	v_lshl_add_u64 v[30:31], v[24:25], 0, s[100:101]
	global_store_dwordx2 v[30:31], v[22:23], off
	s_waitcnt vmcnt(35)
	v_lshlrev_b32_e32 v18, 16, v56
	v_and_b32_e32 v19, 0xffff0000, v56
	v_lshlrev_b32_e32 v20, 16, v57
	v_and_b32_e32 v21, 0xffff0000, v57
	v_pk_fma_f32 v[8:9], v[8:9], v[58:59], v[18:19]
	v_pk_fma_f32 v[10:11], v[10:11], v[60:61], v[20:21]
	s_mov_b32 s100, 0x140000
	v_lshl_add_u64 v[28:29], v[24:25], 0, s[100:101]
	global_load_dwordx2 v[56:57], v[28:29], off
	s_mov_b32 s100, 0x2800
	v_lshl_add_u64 v[28:29], v[26:27], 0, s[100:101]
	global_load_dwordx4 v[58:61], v[28:29], off
	v_cvt_pk_bf16_f32 v22, v8, v9
	v_cvt_pk_bf16_f32 v23, v10, v11
	s_mov_b32 s100, 0x50000
	v_lshl_add_u64 v[30:31], v[24:25], 0, s[100:101]
	global_store_dwordx2 v[30:31], v[22:23], off
	s_waitcnt vmcnt(36)
	v_lshlrev_b32_e32 v18, 16, v62
	v_and_b32_e32 v19, 0xffff0000, v62
	v_lshlrev_b32_e32 v20, 16, v63
	v_and_b32_e32 v21, 0xffff0000, v63
	v_pk_fma_f32 v[8:9], v[8:9], v[64:65], v[18:19]
	v_pk_fma_f32 v[10:11], v[10:11], v[66:67], v[20:21]
	s_mov_b32 s100, 0x150000
	v_lshl_add_u64 v[28:29], v[24:25], 0, s[100:101]
	global_load_dwordx2 v[62:63], v[28:29], off
	s_mov_b32 s100, 0x2a00
	v_lshl_add_u64 v[28:29], v[26:27], 0, s[100:101]
	global_load_dwordx4 v[64:67], v[28:29], off
	v_cvt_pk_bf16_f32 v22, v8, v9
	v_cvt_pk_bf16_f32 v23, v10, v11
	s_mov_b32 s100, 0x60000
	v_lshl_add_u64 v[30:31], v[24:25], 0, s[100:101]
	global_store_dwordx2 v[30:31], v[22:23], off
	s_waitcnt vmcnt(37)
	v_lshlrev_b32_e32 v18, 16, v68
	v_and_b32_e32 v19, 0xffff0000, v68
	v_lshlrev_b32_e32 v20, 16, v69
	v_and_b32_e32 v21, 0xffff0000, v69
	v_pk_fma_f32 v[8:9], v[8:9], v[70:71], v[18:19]
	v_pk_fma_f32 v[10:11], v[10:11], v[72:73], v[20:21]
	s_mov_b32 s100, 0x160000
	v_lshl_add_u64 v[28:29], v[24:25], 0, s[100:101]
	global_load_dwordx2 v[68:69], v[28:29], off
	s_mov_b32 s100, 0x2c00
	v_lshl_add_u64 v[28:29], v[26:27], 0, s[100:101]
	global_load_dwordx4 v[70:73], v[28:29], off
	v_cvt_pk_bf16_f32 v22, v8, v9
	v_cvt_pk_bf16_f32 v23, v10, v11
	s_mov_b32 s100, 0x70000
	v_lshl_add_u64 v[30:31], v[24:25], 0, s[100:101]
	global_store_dwordx2 v[30:31], v[22:23], off
	s_waitcnt vmcnt(38)
	v_lshlrev_b32_e32 v18, 16, v74
	v_and_b32_e32 v19, 0xffff0000, v74
	v_lshlrev_b32_e32 v20, 16, v75
	v_and_b32_e32 v21, 0xffff0000, v75
	v_pk_fma_f32 v[8:9], v[8:9], v[76:77], v[18:19]
	v_pk_fma_f32 v[10:11], v[10:11], v[78:79], v[20:21]
	s_mov_b32 s100, 0x170000
	v_lshl_add_u64 v[28:29], v[24:25], 0, s[100:101]
	global_load_dwordx2 v[74:75], v[28:29], off
	s_mov_b32 s100, 0x2e00
	v_lshl_add_u64 v[28:29], v[26:27], 0, s[100:101]
	global_load_dwordx4 v[76:79], v[28:29], off
	v_cvt_pk_bf16_f32 v22, v8, v9
	v_cvt_pk_bf16_f32 v23, v10, v11
	s_mov_b32 s100, 0x80000
	v_lshl_add_u64 v[30:31], v[24:25], 0, s[100:101]
	global_store_dwordx2 v[30:31], v[22:23], off
	s_waitcnt vmcnt(39)
	v_lshlrev_b32_e32 v18, 16, v80
	v_and_b32_e32 v19, 0xffff0000, v80
	v_lshlrev_b32_e32 v20, 16, v81
	v_and_b32_e32 v21, 0xffff0000, v81
	v_pk_fma_f32 v[8:9], v[8:9], v[82:83], v[18:19]
	v_pk_fma_f32 v[10:11], v[10:11], v[84:85], v[20:21]
	s_mov_b32 s100, 0x180000
	v_lshl_add_u64 v[28:29], v[24:25], 0, s[100:101]
	global_load_dwordx2 v[80:81], v[28:29], off
	s_mov_b32 s100, 0x3000
	v_lshl_add_u64 v[28:29], v[26:27], 0, s[100:101]
	global_load_dwordx4 v[82:85], v[28:29], off
	v_cvt_pk_bf16_f32 v22, v8, v9
	v_cvt_pk_bf16_f32 v23, v10, v11
	s_mov_b32 s100, 0x90000
	v_lshl_add_u64 v[30:31], v[24:25], 0, s[100:101]
	global_store_dwordx2 v[30:31], v[22:23], off
	s_waitcnt vmcnt(40)
	v_lshlrev_b32_e32 v18, 16, v86
	v_and_b32_e32 v19, 0xffff0000, v86
	v_lshlrev_b32_e32 v20, 16, v87
	v_and_b32_e32 v21, 0xffff0000, v87
	v_pk_fma_f32 v[8:9], v[8:9], v[88:89], v[18:19]
	v_pk_fma_f32 v[10:11], v[10:11], v[90:91], v[20:21]
	s_mov_b32 s100, 0x190000
	v_lshl_add_u64 v[28:29], v[24:25], 0, s[100:101]
	global_load_dwordx2 v[86:87], v[28:29], off
	s_mov_b32 s100, 0x3200
	v_lshl_add_u64 v[28:29], v[26:27], 0, s[100:101]
	global_load_dwordx4 v[88:91], v[28:29], off
	v_cvt_pk_bf16_f32 v22, v8, v9
	v_cvt_pk_bf16_f32 v23, v10, v11
	s_mov_b32 s100, 0xa0000
	v_lshl_add_u64 v[30:31], v[24:25], 0, s[100:101]
	global_store_dwordx2 v[30:31], v[22:23], off
	s_waitcnt vmcnt(41)
; __device__ __forceinline__ unsigned pk2(float lo, float hi) { const f32v2_t v = {lo, hi}; const bf16v2_t b = __builtin_convertvector(v, bf16v2_t); return __builtin_bit_cast(unsigned, b); }
; __device__ __forceinline__ float bflo(unsigned w) { return __uint_as_float(w << 16); }
; __device__ __forceinline__ float bfhi(unsigned w) { return __uint_as_float(w & 0xffff0000u); }
; __device__ __forceinline__ int otid() { int t = threadIdx.x; asm volatile("" : "+v"(t)); return t; }
; __device__ __forceinline__ void gla_scan(const Args& a, int G, size_t dst_off = WS_KV) {
;     ...
;     for (int id = blockIdx.x * 512 + otid(); id < 16 * 256 * 32; id += G * 512) {
;         const int bh = id >> 13, v = (id >> 5) & 255, d0 = (id & 31) * 4;
;         float s0 = 0.f, s1 = 0.f, s2 = 0.f, s3 = 0.f;
; #pragma unroll 8
;         for (int n = 0; n < 64; ++n) {
;             const int unit = bh * 64 + n;
;             u32x2* p = (u32x2*)(KV + ((size_t)unit * 256 + v) * 128 + d0);
;             const u32x2 kv = *p; const f32x4 dc = *(const f32x4*)(DEC + (size_t)unit * 128 + d0);
;             u32x2 o; o.x = pk2(s0, s1); o.y = pk2(s2, s3); *(u32x2*)((char*)p + dd) = o;
;             s0 = dc[0] * s0 + bflo(kv.x); s1 = dc[1] * s1 + bfhi(kv.x); s2 = dc[2] * s2 + bflo(kv.y); s3 = dc[3] * s3 + bfhi(kv.y);
;         }
	v_lshlrev_b32_e32 v18, 16, v92
	v_and_b32_e32 v19, 0xffff0000, v92
	v_lshlrev_b32_e32 v20, 16, v93
	v_and_b32_e32 v21, 0xffff0000, v93
	v_pk_fma_f32 v[8:9], v[8:9], v[94:95], v[18:19]
	v_pk_fma_f32 v[10:11], v[10:11], v[96:97], v[20:21]
	s_mov_b32 s100, 0x1a0000
	v_lshl_add_u64 v[28:29], v[24:25], 0, s[100:101]
	global_load_dwordx2 v[92:93], v[28:29], off
	s_mov_b32 s100, 0x3400
	v_lshl_add_u64 v[28:29], v[26:27], 0, s[100:101]
	global_load_dwordx4 v[94:97], v[28:29], off
	v_cvt_pk_bf16_f32 v22, v8, v9
	v_cvt_pk_bf16_f32 v23, v10, v11
	s_mov_b32 s100, 0xb0000
	v_lshl_add_u64 v[30:31], v[24:25], 0, s[100:101]
	global_store_dwordx2 v[30:31], v[22:23], off
	s_waitcnt vmcnt(42)
	v_lshlrev_b32_e32 v18, 16, v98
	v_and_b32_e32 v19, 0xffff0000, v98
	v_lshlrev_b32_e32 v20, 16, v99
	v_and_b32_e32 v21, 0xffff0000, v99
	v_pk_fma_f32 v[8:9], v[8:9], v[100:101], v[18:19]
	v_pk_fma_f32 v[10:11], v[10:11], v[102:103], v[20:21]
	s_mov_b32 s100, 0x1b0000
	v_lshl_add_u64 v[28:29], v[24:25], 0, s[100:101]
	global_load_dwordx2 v[98:99], v[28:29], off
	s_mov_b32 s100, 0x3600
	v_lshl_add_u64 v[28:29], v[26:27], 0, s[100:101]
	global_load_dwordx4 v[100:103], v[28:29], off
	v_cvt_pk_bf16_f32 v22, v8, v9
	v_cvt_pk_bf16_f32 v23, v10, v11
	s_mov_b32 s100, 0xc0000
	v_lshl_add_u64 v[30:31], v[24:25], 0, s[100:101]
	global_store_dwordx2 v[30:31], v[22:23], off
	s_waitcnt vmcnt(43)
	v_lshlrev_b32_e32 v18, 16, v104
	v_and_b32_e32 v19, 0xffff0000, v104
	v_lshlrev_b32_e32 v20, 16, v105
	v_and_b32_e32 v21, 0xffff0000, v105
	v_pk_fma_f32 v[8:9], v[8:9], v[106:107], v[18:19]
	v_pk_fma_f32 v[10:11], v[10:11], v[108:109], v[20:21]
	s_mov_b32 s100, 0x1c0000
	v_lshl_add_u64 v[28:29], v[24:25], 0, s[100:101]
	global_load_dwordx2 v[104:105], v[28:29], off
	s_mov_b32 s100, 0x3800
	v_lshl_add_u64 v[28:29], v[26:27], 0, s[100:101]
	global_load_dwordx4 v[106:109], v[28:29], off
	v_cvt_pk_bf16_f32 v22, v8, v9
	v_cvt_pk_bf16_f32 v23, v10, v11
	s_mov_b32 s100, 0xd0000
	v_lshl_add_u64 v[30:31], v[24:25], 0, s[100:101]
	global_store_dwordx2 v[30:31], v[22:23], off
	s_waitcnt vmcnt(44)
	v_lshlrev_b32_e32 v18, 16, v110
	v_and_b32_e32 v19, 0xffff0000, v110
	v_lshlrev_b32_e32 v20, 16, v111
	v_and_b32_e32 v21, 0xffff0000, v111
	v_pk_fma_f32 v[8:9], v[8:9], v[112:113], v[18:19]
	v_pk_fma_f32 v[10:11], v[10:11], v[114:115], v[20:21]
	s_mov_b32 s100, 0x1d0000
	v_lshl_add_u64 v[28:29], v[24:25], 0, s[100:101]
	global_load_dwordx2 v[110:111], v[28:29], off
	s_mov_b32 s100, 0x3a00
	v_lshl_add_u64 v[28:29], v[26:27], 0, s[100:101]
	global_load_dwordx4 v[112:115], v[28:29], off
	v_cvt_pk_bf16_f32 v22, v8, v9
	v_cvt_pk_bf16_f32 v23, v10, v11
	s_mov_b32 s100, 0xe0000
	v_lshl_add_u64 v[30:31], v[24:25], 0, s[100:101]
	global_store_dwordx2 v[30:31], v[22:23], off
	s_waitcnt vmcnt(45)
	v_lshlrev_b32_e32 v18, 16, v116
	v_and_b32_e32 v19, 0xffff0000, v116
	v_lshlrev_b32_e32 v20, 16, v117
	v_and_b32_e32 v21, 0xffff0000, v117
	v_pk_fma_f32 v[8:9], v[8:9], v[118:119], v[18:19]
	v_pk_fma_f32 v[10:11], v[10:11], v[120:121], v[20:21]
	s_mov_b32 s100, 0x1e0000
	v_lshl_add_u64 v[28:29], v[24:25], 0, s[100:101]
	global_load_dwordx2 v[116:117], v[28:29], off
	s_mov_b32 s100, 0x3c00
	v_lshl_add_u64 v[28:29], v[26:27], 0, s[100:101]
	global_load_dwordx4 v[118:121], v[28:29], off
	v_cvt_pk_bf16_f32 v22, v8, v9
	v_cvt_pk_bf16_f32 v23, v10, v11
	s_mov_b32 s100, 0xf0000
	v_lshl_add_u64 v[30:31], v[24:25], 0, s[100:101]
	global_store_dwordx2 v[30:31], v[22:23], off
	s_waitcnt vmcnt(46)
	v_lshlrev_b32_e32 v18, 16, v122
	v_and_b32_e32 v19, 0xffff0000, v122
	v_lshlrev_b32_e32 v20, 16, v123
	v_and_b32_e32 v21, 0xffff0000, v123
	v_pk_fma_f32 v[8:9], v[8:9], v[124:125], v[18:19]
	v_pk_fma_f32 v[10:11], v[10:11], v[126:127], v[20:21]
	s_mov_b32 s100, 0x1f0000
	v_lshl_add_u64 v[28:29], v[24:25], 0, s[100:101]
	global_load_dwordx2 v[122:123], v[28:29], off
	s_mov_b32 s100, 0x3e00
	v_lshl_add_u64 v[28:29], v[26:27], 0, s[100:101]
	global_load_dwordx4 v[124:127], v[28:29], off
	v_cvt_pk_bf16_f32 v22, v8, v9
	v_cvt_pk_bf16_f32 v23, v10, v11
	s_mov_b32 s100, 0x100000
	v_lshl_add_u64 v[30:31], v[24:25], 0, s[100:101]
	global_store_dwordx2 v[30:31], v[22:23], off
	s_waitcnt vmcnt(46)
	v_lshlrev_b32_e32 v18, 16, v32
	v_and_b32_e32 v19, 0xffff0000, v32
	v_lshlrev_b32_e32 v20, 16, v33
	v_and_b32_e32 v21, 0xffff0000, v33
	v_pk_fma_f32 v[8:9], v[8:9], v[34:35], v[18:19]
	v_pk_fma_f32 v[10:11], v[10:11], v[36:37], v[20:21]
	s_mov_b32 s100, 0x200000
	v_lshl_add_u64 v[28:29], v[24:25], 0, s[100:101]
	global_load_dwordx2 v[32:33], v[28:29], off
	s_mov_b32 s100, 0x4000
	v_lshl_add_u64 v[28:29], v[26:27], 0, s[100:101]
	global_load_dwordx4 v[34:37], v[28:29], off
	v_cvt_pk_bf16_f32 v22, v8, v9
	v_cvt_pk_bf16_f32 v23, v10, v11
	s_mov_b32 s100, 0x110000
	v_lshl_add_u64 v[30:31], v[24:25], 0, s[100:101]
	global_store_dwordx2 v[30:31], v[22:23], off
	s_waitcnt vmcnt(46)
	v_lshlrev_b32_e32 v18, 16, v38
	v_and_b32_e32 v19, 0xffff0000, v38
	v_lshlrev_b32_e32 v20, 16, v39
	v_and_b32_e32 v21, 0xffff0000, v39
	v_pk_fma_f32 v[8:9], v[8:9], v[40:41], v[18:19]
	v_pk_fma_f32 v[10:11], v[10:11], v[42:43], v[20:21]
	s_mov_b32 s100, 0x210000
	v_lshl_add_u64 v[28:29], v[24:25], 0, s[100:101]
	global_load_dwordx2 v[38:39], v[28:29], off
	s_mov_b32 s100, 0x4200
	v_lshl_add_u64 v[28:29], v[26:27], 0, s[100:101]
	global_load_dwordx4 v[40:43], v[28:29], off
	v_cvt_pk_bf16_f32 v22, v8, v9
	v_cvt_pk_bf16_f32 v23, v10, v11
	s_mov_b32 s100, 0x120000
	v_lshl_add_u64 v[30:31], v[24:25], 0, s[100:101]
	global_store_dwordx2 v[30:31], v[22:23], off
	s_waitcnt vmcnt(46)
; __device__ __forceinline__ unsigned pk2(float lo, float hi) { const f32v2_t v = {lo, hi}; const bf16v2_t b = __builtin_convertvector(v, bf16v2_t); return __builtin_bit_cast(unsigned, b); }
; __device__ __forceinline__ float bflo(unsigned w) { return __uint_as_float(w << 16); }
; __device__ __forceinline__ float bfhi(unsigned w) { return __uint_as_float(w & 0xffff0000u); }
; __device__ __forceinline__ int otid() { int t = threadIdx.x; asm volatile("" : "+v"(t)); return t; }
; __device__ __forceinline__ void gla_scan(const Args& a, int G, size_t dst_off = WS_KV) {
;     ...
;     for (int id = blockIdx.x * 512 + otid(); id < 16 * 256 * 32; id += G * 512) {
;         const int bh = id >> 13, v = (id >> 5) & 255, d0 = (id & 31) * 4;
;         float s0 = 0.f, s1 = 0.f, s2 = 0.f, s3 = 0.f;
; #pragma unroll 8
;         for (int n = 0; n < 64; ++n) {
;             const int unit = bh * 64 + n;
;             u32x2* p = (u32x2*)(KV + ((size_t)unit * 256 + v) * 128 + d0);
;             const u32x2 kv = *p; const f32x4 dc = *(const f32x4*)(DEC + (size_t)unit * 128 + d0);
;             u32x2 o; o.x = pk2(s0, s1); o.y = pk2(s2, s3); *(u32x2*)((char*)p + dd) = o;
;             s0 = dc[0] * s0 + bflo(kv.x); s1 = dc[1] * s1 + bfhi(kv.x); s2 = dc[2] * s2 + bflo(kv.y); s3 = dc[3] * s3 + bfhi(kv.y);
;         }
	v_lshlrev_b32_e32 v18, 16, v44
	v_and_b32_e32 v19, 0xffff0000, v44
	v_lshlrev_b32_e32 v20, 16, v45
	v_and_b32_e32 v21, 0xffff0000, v45
	v_pk_fma_f32 v[8:9], v[8:9], v[46:47], v[18:19]
	v_pk_fma_f32 v[10:11], v[10:11], v[48:49], v[20:21]
	s_mov_b32 s100, 0x220000
	v_lshl_add_u64 v[28:29], v[24:25], 0, s[100:101]
	global_load_dwordx2 v[44:45], v[28:29], off
	s_mov_b32 s100, 0x4400
	v_lshl_add_u64 v[28:29], v[26:27], 0, s[100:101]
	global_load_dwordx4 v[46:49], v[28:29], off
	v_cvt_pk_bf16_f32 v22, v8, v9
	v_cvt_pk_bf16_f32 v23, v10, v11
	s_mov_b32 s100, 0x130000
	v_lshl_add_u64 v[30:31], v[24:25], 0, s[100:101]
	global_store_dwordx2 v[30:31], v[22:23], off
	s_waitcnt vmcnt(46)
	v_lshlrev_b32_e32 v18, 16, v50
	v_and_b32_e32 v19, 0xffff0000, v50
	v_lshlrev_b32_e32 v20, 16, v51
	v_and_b32_e32 v21, 0xffff0000, v51
	v_pk_fma_f32 v[8:9], v[8:9], v[52:53], v[18:19]
	v_pk_fma_f32 v[10:11], v[10:11], v[54:55], v[20:21]
	s_mov_b32 s100, 0x230000
	v_lshl_add_u64 v[28:29], v[24:25], 0, s[100:101]
	global_load_dwordx2 v[50:51], v[28:29], off
	s_mov_b32 s100, 0x4600
	v_lshl_add_u64 v[28:29], v[26:27], 0, s[100:101]
	global_load_dwordx4 v[52:55], v[28:29], off
	v_cvt_pk_bf16_f32 v22, v8, v9
	v_cvt_pk_bf16_f32 v23, v10, v11
	s_mov_b32 s100, 0x140000
	v_lshl_add_u64 v[30:31], v[24:25], 0, s[100:101]
	global_store_dwordx2 v[30:31], v[22:23], off
	s_waitcnt vmcnt(46)
	v_lshlrev_b32_e32 v18, 16, v56
	v_and_b32_e32 v19, 0xffff0000, v56
	v_lshlrev_b32_e32 v20, 16, v57
	v_and_b32_e32 v21, 0xffff0000, v57
	v_pk_fma_f32 v[8:9], v[8:9], v[58:59], v[18:19]
	v_pk_fma_f32 v[10:11], v[10:11], v[60:61], v[20:21]
	s_mov_b32 s100, 0x240000
	v_lshl_add_u64 v[28:29], v[24:25], 0, s[100:101]
	global_load_dwordx2 v[56:57], v[28:29], off
	s_mov_b32 s100, 0x4800
	v_lshl_add_u64 v[28:29], v[26:27], 0, s[100:101]
	global_load_dwordx4 v[58:61], v[28:29], off
	v_cvt_pk_bf16_f32 v22, v8, v9
	v_cvt_pk_bf16_f32 v23, v10, v11
	s_mov_b32 s100, 0x150000
	v_lshl_add_u64 v[30:31], v[24:25], 0, s[100:101]
	global_store_dwordx2 v[30:31], v[22:23], off
	s_waitcnt vmcnt(46)
	v_lshlrev_b32_e32 v18, 16, v62
	v_and_b32_e32 v19, 0xffff0000, v62
	v_lshlrev_b32_e32 v20, 16, v63
	v_and_b32_e32 v21, 0xffff0000, v63
	v_pk_fma_f32 v[8:9], v[8:9], v[64:65], v[18:19]
	v_pk_fma_f32 v[10:11], v[10:11], v[66:67], v[20:21]
	s_mov_b32 s100, 0x250000
	v_lshl_add_u64 v[28:29], v[24:25], 0, s[100:101]
	global_load_dwordx2 v[62:63], v[28:29], off
	s_mov_b32 s100, 0x4a00
	v_lshl_add_u64 v[28:29], v[26:27], 0, s[100:101]
	global_load_dwordx4 v[64:67], v[28:29], off
	v_cvt_pk_bf16_f32 v22, v8, v9
	v_cvt_pk_bf16_f32 v23, v10, v11
	s_mov_b32 s100, 0x160000
	v_lshl_add_u64 v[30:31], v[24:25], 0, s[100:101]
	global_store_dwordx2 v[30:31], v[22:23], off
	s_waitcnt vmcnt(46)
	v_lshlrev_b32_e32 v18, 16, v68
	v_and_b32_e32 v19, 0xffff0000, v68
	v_lshlrev_b32_e32 v20, 16, v69
	v_and_b32_e32 v21, 0xffff0000, v69
	v_pk_fma_f32 v[8:9], v[8:9], v[70:71], v[18:19]
	v_pk_fma_f32 v[10:11], v[10:11], v[72:73], v[20:21]
	s_mov_b32 s100, 0x260000
	v_lshl_add_u64 v[28:29], v[24:25], 0, s[100:101]
	global_load_dwordx2 v[68:69], v[28:29], off
	s_mov_b32 s100, 0x4c00
	v_lshl_add_u64 v[28:29], v[26:27], 0, s[100:101]
	global_load_dwordx4 v[70:73], v[28:29], off
	v_cvt_pk_bf16_f32 v22, v8, v9
	v_cvt_pk_bf16_f32 v23, v10, v11
	s_mov_b32 s100, 0x170000
	v_lshl_add_u64 v[30:31], v[24:25], 0, s[100:101]
	global_store_dwordx2 v[30:31], v[22:23], off
	s_waitcnt vmcnt(46)
	v_lshlrev_b32_e32 v18, 16, v74
	v_and_b32_e32 v19, 0xffff0000, v74
	v_lshlrev_b32_e32 v20, 16, v75
	v_and_b32_e32 v21, 0xffff0000, v75
	v_pk_fma_f32 v[8:9], v[8:9], v[76:77], v[18:19]
	v_pk_fma_f32 v[10:11], v[10:11], v[78:79], v[20:21]
	s_mov_b32 s100, 0x270000
	v_lshl_add_u64 v[28:29], v[24:25], 0, s[100:101]
	global_load_dwordx2 v[74:75], v[28:29], off
	s_mov_b32 s100, 0x4e00
	v_lshl_add_u64 v[28:29], v[26:27], 0, s[100:101]
	global_load_dwordx4 v[76:79], v[28:29], off
	v_cvt_pk_bf16_f32 v22, v8, v9
	v_cvt_pk_bf16_f32 v23, v10, v11
	s_mov_b32 s100, 0x180000
	v_lshl_add_u64 v[30:31], v[24:25], 0, s[100:101]
	global_store_dwordx2 v[30:31], v[22:23], off
	s_waitcnt vmcnt(46)
	v_lshlrev_b32_e32 v18, 16, v80
	v_and_b32_e32 v19, 0xffff0000, v80
	v_lshlrev_b32_e32 v20, 16, v81
	v_and_b32_e32 v21, 0xffff0000, v81
	v_pk_fma_f32 v[8:9], v[8:9], v[82:83], v[18:19]
	v_pk_fma_f32 v[10:11], v[10:11], v[84:85], v[20:21]
	s_mov_b32 s100, 0x280000
	v_lshl_add_u64 v[28:29], v[24:25], 0, s[100:101]
	global_load_dwordx2 v[80:81], v[28:29], off
	s_mov_b32 s100, 0x5000
	v_lshl_add_u64 v[28:29], v[26:27], 0, s[100:101]
	global_load_dwordx4 v[82:85], v[28:29], off
	v_cvt_pk_bf16_f32 v22, v8, v9
	v_cvt_pk_bf16_f32 v23, v10, v11
	s_mov_b32 s100, 0x190000
	v_lshl_add_u64 v[30:31], v[24:25], 0, s[100:101]
	global_store_dwordx2 v[30:31], v[22:23], off
	s_waitcnt vmcnt(46)
	v_lshlrev_b32_e32 v18, 16, v86
	v_and_b32_e32 v19, 0xffff0000, v86
	v_lshlrev_b32_e32 v20, 16, v87
	v_and_b32_e32 v21, 0xffff0000, v87
	v_pk_fma_f32 v[8:9], v[8:9], v[88:89], v[18:19]
	v_pk_fma_f32 v[10:11], v[10:11], v[90:91], v[20:21]
	s_mov_b32 s100, 0x290000
	v_lshl_add_u64 v[28:29], v[24:25], 0, s[100:101]
	global_load_dwordx2 v[86:87], v[28:29], off
	s_mov_b32 s100, 0x5200
	v_lshl_add_u64 v[28:29], v[26:27], 0, s[100:101]
	global_load_dwordx4 v[88:91], v[28:29], off
	v_cvt_pk_bf16_f32 v22, v8, v9
	v_cvt_pk_bf16_f32 v23, v10, v11
	s_mov_b32 s100, 0x1a0000
	v_lshl_add_u64 v[30:31], v[24:25], 0, s[100:101]
	global_store_dwordx2 v[30:31], v[22:23], off
	s_waitcnt vmcnt(46)
; __device__ __forceinline__ unsigned pk2(float lo, float hi) { const f32v2_t v = {lo, hi}; const bf16v2_t b = __builtin_convertvector(v, bf16v2_t); return __builtin_bit_cast(unsigned, b); }
; __device__ __forceinline__ float bflo(unsigned w) { return __uint_as_float(w << 16); }
; __device__ __forceinline__ float bfhi(unsigned w) { return __uint_as_float(w & 0xffff0000u); }
; __device__ __forceinline__ int otid() { int t = threadIdx.x; asm volatile("" : "+v"(t)); return t; }
; __device__ __forceinline__ void gla_scan(const Args& a, int G, size_t dst_off = WS_KV) {
;     ...
;     for (int id = blockIdx.x * 512 + otid(); id < 16 * 256 * 32; id += G * 512) {
;         const int bh = id >> 13, v = (id >> 5) & 255, d0 = (id & 31) * 4;
;         float s0 = 0.f, s1 = 0.f, s2 = 0.f, s3 = 0.f;
; #pragma unroll 8
;         for (int n = 0; n < 64; ++n) {
;             const int unit = bh * 64 + n;
;             u32x2* p = (u32x2*)(KV + ((size_t)unit * 256 + v) * 128 + d0);
;             const u32x2 kv = *p; const f32x4 dc = *(const f32x4*)(DEC + (size_t)unit * 128 + d0);
;             u32x2 o; o.x = pk2(s0, s1); o.y = pk2(s2, s3); *(u32x2*)((char*)p + dd) = o;
;             s0 = dc[0] * s0 + bflo(kv.x); s1 = dc[1] * s1 + bfhi(kv.x); s2 = dc[2] * s2 + bflo(kv.y); s3 = dc[3] * s3 + bfhi(kv.y);
;         }
	v_lshlrev_b32_e32 v18, 16, v92
	v_and_b32_e32 v19, 0xffff0000, v92
	v_lshlrev_b32_e32 v20, 16, v93
	v_and_b32_e32 v21, 0xffff0000, v93
	v_pk_fma_f32 v[8:9], v[8:9], v[94:95], v[18:19]
	v_pk_fma_f32 v[10:11], v[10:11], v[96:97], v[20:21]
	s_mov_b32 s100, 0x2a0000
	v_lshl_add_u64 v[28:29], v[24:25], 0, s[100:101]
	global_load_dwordx2 v[92:93], v[28:29], off
	s_mov_b32 s100, 0x5400
	v_lshl_add_u64 v[28:29], v[26:27], 0, s[100:101]
	global_load_dwordx4 v[94:97], v[28:29], off
	v_cvt_pk_bf16_f32 v22, v8, v9
	v_cvt_pk_bf16_f32 v23, v10, v11
	s_mov_b32 s100, 0x1b0000
	v_lshl_add_u64 v[30:31], v[24:25], 0, s[100:101]
	global_store_dwordx2 v[30:31], v[22:23], off
	s_waitcnt vmcnt(46)
	v_lshlrev_b32_e32 v18, 16, v98
	v_and_b32_e32 v19, 0xffff0000, v98
	v_lshlrev_b32_e32 v20, 16, v99
	v_and_b32_e32 v21, 0xffff0000, v99
	v_pk_fma_f32 v[8:9], v[8:9], v[100:101], v[18:19]
	v_pk_fma_f32 v[10:11], v[10:11], v[102:103], v[20:21]
	s_mov_b32 s100, 0x2b0000
	v_lshl_add_u64 v[28:29], v[24:25], 0, s[100:101]
	global_load_dwordx2 v[98:99], v[28:29], off
	s_mov_b32 s100, 0x5600
	v_lshl_add_u64 v[28:29], v[26:27], 0, s[100:101]
	global_load_dwordx4 v[100:103], v[28:29], off
	v_cvt_pk_bf16_f32 v22, v8, v9
	v_cvt_pk_bf16_f32 v23, v10, v11
	s_mov_b32 s100, 0x1c0000
	v_lshl_add_u64 v[30:31], v[24:25], 0, s[100:101]
	global_store_dwordx2 v[30:31], v[22:23], off
	s_waitcnt vmcnt(46)
	v_lshlrev_b32_e32 v18, 16, v104
	v_and_b32_e32 v19, 0xffff0000, v104
	v_lshlrev_b32_e32 v20, 16, v105
	v_and_b32_e32 v21, 0xffff0000, v105
	v_pk_fma_f32 v[8:9], v[8:9], v[106:107], v[18:19]
	v_pk_fma_f32 v[10:11], v[10:11], v[108:109], v[20:21]
	s_mov_b32 s100, 0x2c0000
	v_lshl_add_u64 v[28:29], v[24:25], 0, s[100:101]
	global_load_dwordx2 v[104:105], v[28:29], off
	s_mov_b32 s100, 0x5800
	v_lshl_add_u64 v[28:29], v[26:27], 0, s[100:101]
	global_load_dwordx4 v[106:109], v[28:29], off
	v_cvt_pk_bf16_f32 v22, v8, v9
	v_cvt_pk_bf16_f32 v23, v10, v11
	s_mov_b32 s100, 0x1d0000
	v_lshl_add_u64 v[30:31], v[24:25], 0, s[100:101]
	global_store_dwordx2 v[30:31], v[22:23], off
	s_waitcnt vmcnt(46)
	v_lshlrev_b32_e32 v18, 16, v110
	v_and_b32_e32 v19, 0xffff0000, v110
	v_lshlrev_b32_e32 v20, 16, v111
	v_and_b32_e32 v21, 0xffff0000, v111
	v_pk_fma_f32 v[8:9], v[8:9], v[112:113], v[18:19]
	v_pk_fma_f32 v[10:11], v[10:11], v[114:115], v[20:21]
	s_mov_b32 s100, 0x2d0000
	v_lshl_add_u64 v[28:29], v[24:25], 0, s[100:101]
	global_load_dwordx2 v[110:111], v[28:29], off
	s_mov_b32 s100, 0x5a00
	v_lshl_add_u64 v[28:29], v[26:27], 0, s[100:101]
	global_load_dwordx4 v[112:115], v[28:29], off
	v_cvt_pk_bf16_f32 v22, v8, v9
	v_cvt_pk_bf16_f32 v23, v10, v11
	s_mov_b32 s100, 0x1e0000
	v_lshl_add_u64 v[30:31], v[24:25], 0, s[100:101]
	global_store_dwordx2 v[30:31], v[22:23], off
	s_waitcnt vmcnt(46)
	v_lshlrev_b32_e32 v18, 16, v116
	v_and_b32_e32 v19, 0xffff0000, v116
	v_lshlrev_b32_e32 v20, 16, v117
	v_and_b32_e32 v21, 0xffff0000, v117
	v_pk_fma_f32 v[8:9], v[8:9], v[118:119], v[18:19]
	v_pk_fma_f32 v[10:11], v[10:11], v[120:121], v[20:21]
	s_mov_b32 s100, 0x2e0000
	v_lshl_add_u64 v[28:29], v[24:25], 0, s[100:101]
	global_load_dwordx2 v[116:117], v[28:29], off
	s_mov_b32 s100, 0x5c00
	v_lshl_add_u64 v[28:29], v[26:27], 0, s[100:101]
	global_load_dwordx4 v[118:121], v[28:29], off
	v_cvt_pk_bf16_f32 v22, v8, v9
	v_cvt_pk_bf16_f32 v23, v10, v11
	s_mov_b32 s100, 0x1f0000
	v_lshl_add_u64 v[30:31], v[24:25], 0, s[100:101]
	global_store_dwordx2 v[30:31], v[22:23], off
	s_waitcnt vmcnt(46)
	v_lshlrev_b32_e32 v18, 16, v122
	v_and_b32_e32 v19, 0xffff0000, v122
	v_lshlrev_b32_e32 v20, 16, v123
	v_and_b32_e32 v21, 0xffff0000, v123
	v_pk_fma_f32 v[8:9], v[8:9], v[124:125], v[18:19]
	v_pk_fma_f32 v[10:11], v[10:11], v[126:127], v[20:21]
	s_mov_b32 s100, 0x2f0000
	v_lshl_add_u64 v[28:29], v[24:25], 0, s[100:101]
	global_load_dwordx2 v[122:123], v[28:29], off
	s_mov_b32 s100, 0x5e00
	v_lshl_add_u64 v[28:29], v[26:27], 0, s[100:101]
	global_load_dwordx4 v[124:127], v[28:29], off
	v_cvt_pk_bf16_f32 v22, v8, v9
	v_cvt_pk_bf16_f32 v23, v10, v11
	s_mov_b32 s100, 0x200000
	v_lshl_add_u64 v[30:31], v[24:25], 0, s[100:101]
	global_store_dwordx2 v[30:31], v[22:23], off
	s_waitcnt vmcnt(46)
	v_lshlrev_b32_e32 v18, 16, v32
	v_and_b32_e32 v19, 0xffff0000, v32
	v_lshlrev_b32_e32 v20, 16, v33
	v_and_b32_e32 v21, 0xffff0000, v33
	v_pk_fma_f32 v[8:9], v[8:9], v[34:35], v[18:19]
	v_pk_fma_f32 v[10:11], v[10:11], v[36:37], v[20:21]
	s_mov_b32 s100, 0x300000
	v_lshl_add_u64 v[28:29], v[24:25], 0, s[100:101]
	global_load_dwordx2 v[32:33], v[28:29], off
	s_mov_b32 s100, 0x6000
	v_lshl_add_u64 v[28:29], v[26:27], 0, s[100:101]
	global_load_dwordx4 v[34:37], v[28:29], off
	v_cvt_pk_bf16_f32 v22, v8, v9
	v_cvt_pk_bf16_f32 v23, v10, v11
	s_mov_b32 s100, 0x210000
	v_lshl_add_u64 v[30:31], v[24:25], 0, s[100:101]
	global_store_dwordx2 v[30:31], v[22:23], off
	s_waitcnt vmcnt(46)
	v_lshlrev_b32_e32 v18, 16, v38
	v_and_b32_e32 v19, 0xffff0000, v38
	v_lshlrev_b32_e32 v20, 16, v39
	v_and_b32_e32 v21, 0xffff0000, v39
	v_pk_fma_f32 v[8:9], v[8:9], v[40:41], v[18:19]
	v_pk_fma_f32 v[10:11], v[10:11], v[42:43], v[20:21]
	s_mov_b32 s100, 0x310000
	v_lshl_add_u64 v[28:29], v[24:25], 0, s[100:101]
	global_load_dwordx2 v[38:39], v[28:29], off
	s_mov_b32 s100, 0x6200
	v_lshl_add_u64 v[28:29], v[26:27], 0, s[100:101]
	global_load_dwordx4 v[40:43], v[28:29], off
	v_cvt_pk_bf16_f32 v22, v8, v9
	v_cvt_pk_bf16_f32 v23, v10, v11
	s_mov_b32 s100, 0x220000
	v_lshl_add_u64 v[30:31], v[24:25], 0, s[100:101]
	global_store_dwordx2 v[30:31], v[22:23], off
	s_waitcnt vmcnt(46)
; __device__ __forceinline__ unsigned pk2(float lo, float hi) { const f32v2_t v = {lo, hi}; const bf16v2_t b = __builtin_convertvector(v, bf16v2_t); return __builtin_bit_cast(unsigned, b); }
; __device__ __forceinline__ float bflo(unsigned w) { return __uint_as_float(w << 16); }
; __device__ __forceinline__ float bfhi(unsigned w) { return __uint_as_float(w & 0xffff0000u); }
; __device__ __forceinline__ int otid() { int t = threadIdx.x; asm volatile("" : "+v"(t)); return t; }
; __device__ __forceinline__ void gla_scan(const Args& a, int G, size_t dst_off = WS_KV) {
;     ...
;     for (int id = blockIdx.x * 512 + otid(); id < 16 * 256 * 32; id += G * 512) {
;         const int bh = id >> 13, v = (id >> 5) & 255, d0 = (id & 31) * 4;
;         float s0 = 0.f, s1 = 0.f, s2 = 0.f, s3 = 0.f;
; #pragma unroll 8
;         for (int n = 0; n < 64; ++n) {
;             const int unit = bh * 64 + n;
;             u32x2* p = (u32x2*)(KV + ((size_t)unit * 256 + v) * 128 + d0);
;             const u32x2 kv = *p; const f32x4 dc = *(const f32x4*)(DEC + (size_t)unit * 128 + d0);
;             u32x2 o; o.x = pk2(s0, s1); o.y = pk2(s2, s3); *(u32x2*)((char*)p + dd) = o;
;             s0 = dc[0] * s0 + bflo(kv.x); s1 = dc[1] * s1 + bfhi(kv.x); s2 = dc[2] * s2 + bflo(kv.y); s3 = dc[3] * s3 + bfhi(kv.y);
;         }
	v_lshlrev_b32_e32 v18, 16, v44
	v_and_b32_e32 v19, 0xffff0000, v44
	v_lshlrev_b32_e32 v20, 16, v45
	v_and_b32_e32 v21, 0xffff0000, v45
	v_pk_fma_f32 v[8:9], v[8:9], v[46:47], v[18:19]
	v_pk_fma_f32 v[10:11], v[10:11], v[48:49], v[20:21]
	s_mov_b32 s100, 0x320000
	v_lshl_add_u64 v[28:29], v[24:25], 0, s[100:101]
	global_load_dwordx2 v[44:45], v[28:29], off
	s_mov_b32 s100, 0x6400
	v_lshl_add_u64 v[28:29], v[26:27], 0, s[100:101]
	global_load_dwordx4 v[46:49], v[28:29], off
	v_cvt_pk_bf16_f32 v22, v8, v9
	v_cvt_pk_bf16_f32 v23, v10, v11
	s_mov_b32 s100, 0x230000
	v_lshl_add_u64 v[30:31], v[24:25], 0, s[100:101]
	global_store_dwordx2 v[30:31], v[22:23], off
	s_waitcnt vmcnt(46)
	v_lshlrev_b32_e32 v18, 16, v50
	v_and_b32_e32 v19, 0xffff0000, v50
	v_lshlrev_b32_e32 v20, 16, v51
	v_and_b32_e32 v21, 0xffff0000, v51
	v_pk_fma_f32 v[8:9], v[8:9], v[52:53], v[18:19]
	v_pk_fma_f32 v[10:11], v[10:11], v[54:55], v[20:21]
	s_mov_b32 s100, 0x330000
	v_lshl_add_u64 v[28:29], v[24:25], 0, s[100:101]
	global_load_dwordx2 v[50:51], v[28:29], off
	s_mov_b32 s100, 0x6600
	v_lshl_add_u64 v[28:29], v[26:27], 0, s[100:101]
	global_load_dwordx4 v[52:55], v[28:29], off
	v_cvt_pk_bf16_f32 v22, v8, v9
	v_cvt_pk_bf16_f32 v23, v10, v11
	s_mov_b32 s100, 0x240000
	v_lshl_add_u64 v[30:31], v[24:25], 0, s[100:101]
	global_store_dwordx2 v[30:31], v[22:23], off
	s_waitcnt vmcnt(46)
	v_lshlrev_b32_e32 v18, 16, v56
	v_and_b32_e32 v19, 0xffff0000, v56
	v_lshlrev_b32_e32 v20, 16, v57
	v_and_b32_e32 v21, 0xffff0000, v57
	v_pk_fma_f32 v[8:9], v[8:9], v[58:59], v[18:19]
	v_pk_fma_f32 v[10:11], v[10:11], v[60:61], v[20:21]
	s_mov_b32 s100, 0x340000
	v_lshl_add_u64 v[28:29], v[24:25], 0, s[100:101]
	global_load_dwordx2 v[56:57], v[28:29], off
	s_mov_b32 s100, 0x6800
	v_lshl_add_u64 v[28:29], v[26:27], 0, s[100:101]
	global_load_dwordx4 v[58:61], v[28:29], off
	v_cvt_pk_bf16_f32 v22, v8, v9
	v_cvt_pk_bf16_f32 v23, v10, v11
	s_mov_b32 s100, 0x250000
	v_lshl_add_u64 v[30:31], v[24:25], 0, s[100:101]
	global_store_dwordx2 v[30:31], v[22:23], off
	s_waitcnt vmcnt(46)
	v_lshlrev_b32_e32 v18, 16, v62
	v_and_b32_e32 v19, 0xffff0000, v62
	v_lshlrev_b32_e32 v20, 16, v63
	v_and_b32_e32 v21, 0xffff0000, v63
	v_pk_fma_f32 v[8:9], v[8:9], v[64:65], v[18:19]
	v_pk_fma_f32 v[10:11], v[10:11], v[66:67], v[20:21]
	s_mov_b32 s100, 0x350000
	v_lshl_add_u64 v[28:29], v[24:25], 0, s[100:101]
	global_load_dwordx2 v[62:63], v[28:29], off
	s_mov_b32 s100, 0x6a00
	v_lshl_add_u64 v[28:29], v[26:27], 0, s[100:101]
	global_load_dwordx4 v[64:67], v[28:29], off
	v_cvt_pk_bf16_f32 v22, v8, v9
	v_cvt_pk_bf16_f32 v23, v10, v11
	s_mov_b32 s100, 0x260000
	v_lshl_add_u64 v[30:31], v[24:25], 0, s[100:101]
	global_store_dwordx2 v[30:31], v[22:23], off
	s_waitcnt vmcnt(46)
	v_lshlrev_b32_e32 v18, 16, v68
	v_and_b32_e32 v19, 0xffff0000, v68
	v_lshlrev_b32_e32 v20, 16, v69
	v_and_b32_e32 v21, 0xffff0000, v69
	v_pk_fma_f32 v[8:9], v[8:9], v[70:71], v[18:19]
	v_pk_fma_f32 v[10:11], v[10:11], v[72:73], v[20:21]
	s_mov_b32 s100, 0x360000
	v_lshl_add_u64 v[28:29], v[24:25], 0, s[100:101]
	global_load_dwordx2 v[68:69], v[28:29], off
	s_mov_b32 s100, 0x6c00
	v_lshl_add_u64 v[28:29], v[26:27], 0, s[100:101]
	global_load_dwordx4 v[70:73], v[28:29], off
	v_cvt_pk_bf16_f32 v22, v8, v9
	v_cvt_pk_bf16_f32 v23, v10, v11
	s_mov_b32 s100, 0x270000
	v_lshl_add_u64 v[30:31], v[24:25], 0, s[100:101]
	global_store_dwordx2 v[30:31], v[22:23], off
	s_waitcnt vmcnt(46)
	v_lshlrev_b32_e32 v18, 16, v74
	v_and_b32_e32 v19, 0xffff0000, v74
	v_lshlrev_b32_e32 v20, 16, v75
	v_and_b32_e32 v21, 0xffff0000, v75
	v_pk_fma_f32 v[8:9], v[8:9], v[76:77], v[18:19]
	v_pk_fma_f32 v[10:11], v[10:11], v[78:79], v[20:21]
	s_mov_b32 s100, 0x370000
	v_lshl_add_u64 v[28:29], v[24:25], 0, s[100:101]
	global_load_dwordx2 v[74:75], v[28:29], off
	s_mov_b32 s100, 0x6e00
	v_lshl_add_u64 v[28:29], v[26:27], 0, s[100:101]
	global_load_dwordx4 v[76:79], v[28:29], off
	v_cvt_pk_bf16_f32 v22, v8, v9
	v_cvt_pk_bf16_f32 v23, v10, v11
	s_mov_b32 s100, 0x280000
	v_lshl_add_u64 v[30:31], v[24:25], 0, s[100:101]
	global_store_dwordx2 v[30:31], v[22:23], off
	s_waitcnt vmcnt(46)
	v_lshlrev_b32_e32 v18, 16, v80
	v_and_b32_e32 v19, 0xffff0000, v80
	v_lshlrev_b32_e32 v20, 16, v81
	v_and_b32_e32 v21, 0xffff0000, v81
	v_pk_fma_f32 v[8:9], v[8:9], v[82:83], v[18:19]
	v_pk_fma_f32 v[10:11], v[10:11], v[84:85], v[20:21]
	s_mov_b32 s100, 0x380000
	v_lshl_add_u64 v[28:29], v[24:25], 0, s[100:101]
	global_load_dwordx2 v[80:81], v[28:29], off
	s_mov_b32 s100, 0x7000
	v_lshl_add_u64 v[28:29], v[26:27], 0, s[100:101]
	global_load_dwordx4 v[82:85], v[28:29], off
	v_cvt_pk_bf16_f32 v22, v8, v9
	v_cvt_pk_bf16_f32 v23, v10, v11
	s_mov_b32 s100, 0x290000
	v_lshl_add_u64 v[30:31], v[24:25], 0, s[100:101]
	global_store_dwordx2 v[30:31], v[22:23], off
	s_waitcnt vmcnt(46)
	v_lshlrev_b32_e32 v18, 16, v86
	v_and_b32_e32 v19, 0xffff0000, v86
	v_lshlrev_b32_e32 v20, 16, v87
	v_and_b32_e32 v21, 0xffff0000, v87
	v_pk_fma_f32 v[8:9], v[8:9], v[88:89], v[18:19]
	v_pk_fma_f32 v[10:11], v[10:11], v[90:91], v[20:21]
	s_mov_b32 s100, 0x390000
	v_lshl_add_u64 v[28:29], v[24:25], 0, s[100:101]
	global_load_dwordx2 v[86:87], v[28:29], off
	s_mov_b32 s100, 0x7200
	v_lshl_add_u64 v[28:29], v[26:27], 0, s[100:101]
	global_load_dwordx4 v[88:91], v[28:29], off
	v_cvt_pk_bf16_f32 v22, v8, v9
	v_cvt_pk_bf16_f32 v23, v10, v11
	s_mov_b32 s100, 0x2a0000
	v_lshl_add_u64 v[30:31], v[24:25], 0, s[100:101]
	global_store_dwordx2 v[30:31], v[22:23], off
	s_waitcnt vmcnt(46)
; __device__ __forceinline__ unsigned pk2(float lo, float hi) { const f32v2_t v = {lo, hi}; const bf16v2_t b = __builtin_convertvector(v, bf16v2_t); return __builtin_bit_cast(unsigned, b); }
; __device__ __forceinline__ float bflo(unsigned w) { return __uint_as_float(w << 16); }
; __device__ __forceinline__ float bfhi(unsigned w) { return __uint_as_float(w & 0xffff0000u); }
; __device__ __forceinline__ int otid() { int t = threadIdx.x; asm volatile("" : "+v"(t)); return t; }
; __device__ __forceinline__ void gla_scan(const Args& a, int G, size_t dst_off = WS_KV) {
;     ...
;     for (int id = blockIdx.x * 512 + otid(); id < 16 * 256 * 32; id += G * 512) {
;         const int bh = id >> 13, v = (id >> 5) & 255, d0 = (id & 31) * 4;
;         float s0 = 0.f, s1 = 0.f, s2 = 0.f, s3 = 0.f;
; #pragma unroll 8
;         for (int n = 0; n < 64; ++n) {
;             const int unit = bh * 64 + n;
;             u32x2* p = (u32x2*)(KV + ((size_t)unit * 256 + v) * 128 + d0);
;             const u32x2 kv = *p; const f32x4 dc = *(const f32x4*)(DEC + (size_t)unit * 128 + d0);
;             u32x2 o; o.x = pk2(s0, s1); o.y = pk2(s2, s3); *(u32x2*)((char*)p + dd) = o;
;             s0 = dc[0] * s0 + bflo(kv.x); s1 = dc[1] * s1 + bfhi(kv.x); s2 = dc[2] * s2 + bflo(kv.y); s3 = dc[3] * s3 + bfhi(kv.y);
;         }
	v_lshlrev_b32_e32 v18, 16, v92
	v_and_b32_e32 v19, 0xffff0000, v92
	v_lshlrev_b32_e32 v20, 16, v93
	v_and_b32_e32 v21, 0xffff0000, v93
	v_pk_fma_f32 v[8:9], v[8:9], v[94:95], v[18:19]
	v_pk_fma_f32 v[10:11], v[10:11], v[96:97], v[20:21]
	s_mov_b32 s100, 0x3a0000
	v_lshl_add_u64 v[28:29], v[24:25], 0, s[100:101]
	global_load_dwordx2 v[92:93], v[28:29], off
	s_mov_b32 s100, 0x7400
	v_lshl_add_u64 v[28:29], v[26:27], 0, s[100:101]
	global_load_dwordx4 v[94:97], v[28:29], off
	v_cvt_pk_bf16_f32 v22, v8, v9
	v_cvt_pk_bf16_f32 v23, v10, v11
	s_mov_b32 s100, 0x2b0000
	v_lshl_add_u64 v[30:31], v[24:25], 0, s[100:101]
	global_store_dwordx2 v[30:31], v[22:23], off
	s_waitcnt vmcnt(46)
	v_lshlrev_b32_e32 v18, 16, v98
	v_and_b32_e32 v19, 0xffff0000, v98
	v_lshlrev_b32_e32 v20, 16, v99
	v_and_b32_e32 v21, 0xffff0000, v99
	v_pk_fma_f32 v[8:9], v[8:9], v[100:101], v[18:19]
	v_pk_fma_f32 v[10:11], v[10:11], v[102:103], v[20:21]
	s_mov_b32 s100, 0x3b0000
	v_lshl_add_u64 v[28:29], v[24:25], 0, s[100:101]
	global_load_dwordx2 v[98:99], v[28:29], off
	s_mov_b32 s100, 0x7600
	v_lshl_add_u64 v[28:29], v[26:27], 0, s[100:101]
	global_load_dwordx4 v[100:103], v[28:29], off
	v_cvt_pk_bf16_f32 v22, v8, v9
	v_cvt_pk_bf16_f32 v23, v10, v11
	s_mov_b32 s100, 0x2c0000
	v_lshl_add_u64 v[30:31], v[24:25], 0, s[100:101]
	global_store_dwordx2 v[30:31], v[22:23], off
	s_waitcnt vmcnt(46)
	v_lshlrev_b32_e32 v18, 16, v104
	v_and_b32_e32 v19, 0xffff0000, v104
	v_lshlrev_b32_e32 v20, 16, v105
	v_and_b32_e32 v21, 0xffff0000, v105
	v_pk_fma_f32 v[8:9], v[8:9], v[106:107], v[18:19]
	v_pk_fma_f32 v[10:11], v[10:11], v[108:109], v[20:21]
	s_mov_b32 s100, 0x3c0000
	v_lshl_add_u64 v[28:29], v[24:25], 0, s[100:101]
	global_load_dwordx2 v[104:105], v[28:29], off
	s_mov_b32 s100, 0x7800
	v_lshl_add_u64 v[28:29], v[26:27], 0, s[100:101]
	global_load_dwordx4 v[106:109], v[28:29], off
	v_cvt_pk_bf16_f32 v22, v8, v9
	v_cvt_pk_bf16_f32 v23, v10, v11
	s_mov_b32 s100, 0x2d0000
	v_lshl_add_u64 v[30:31], v[24:25], 0, s[100:101]
	global_store_dwordx2 v[30:31], v[22:23], off
	s_waitcnt vmcnt(46)
	v_lshlrev_b32_e32 v18, 16, v110
	v_and_b32_e32 v19, 0xffff0000, v110
	v_lshlrev_b32_e32 v20, 16, v111
	v_and_b32_e32 v21, 0xffff0000, v111
	v_pk_fma_f32 v[8:9], v[8:9], v[112:113], v[18:19]
	v_pk_fma_f32 v[10:11], v[10:11], v[114:115], v[20:21]
	s_mov_b32 s100, 0x3d0000
	v_lshl_add_u64 v[28:29], v[24:25], 0, s[100:101]
	global_load_dwordx2 v[110:111], v[28:29], off
	s_mov_b32 s100, 0x7a00
	v_lshl_add_u64 v[28:29], v[26:27], 0, s[100:101]
	global_load_dwordx4 v[112:115], v[28:29], off
	v_cvt_pk_bf16_f32 v22, v8, v9
	v_cvt_pk_bf16_f32 v23, v10, v11
	s_mov_b32 s100, 0x2e0000
	v_lshl_add_u64 v[30:31], v[24:25], 0, s[100:101]
	global_store_dwordx2 v[30:31], v[22:23], off
	s_waitcnt vmcnt(46)
	v_lshlrev_b32_e32 v18, 16, v116
	v_and_b32_e32 v19, 0xffff0000, v116
	v_lshlrev_b32_e32 v20, 16, v117
	v_and_b32_e32 v21, 0xffff0000, v117
	v_pk_fma_f32 v[8:9], v[8:9], v[118:119], v[18:19]
	v_pk_fma_f32 v[10:11], v[10:11], v[120:121], v[20:21]
	s_mov_b32 s100, 0x3e0000
	v_lshl_add_u64 v[28:29], v[24:25], 0, s[100:101]
	global_load_dwordx2 v[116:117], v[28:29], off
	s_mov_b32 s100, 0x7c00
	v_lshl_add_u64 v[28:29], v[26:27], 0, s[100:101]
	global_load_dwordx4 v[118:121], v[28:29], off
	v_cvt_pk_bf16_f32 v22, v8, v9
	v_cvt_pk_bf16_f32 v23, v10, v11
	s_mov_b32 s100, 0x2f0000
	v_lshl_add_u64 v[30:31], v[24:25], 0, s[100:101]
	global_store_dwordx2 v[30:31], v[22:23], off
	s_waitcnt vmcnt(46)
	v_lshlrev_b32_e32 v18, 16, v122
	v_and_b32_e32 v19, 0xffff0000, v122
	v_lshlrev_b32_e32 v20, 16, v123
	v_and_b32_e32 v21, 0xffff0000, v123
	v_pk_fma_f32 v[8:9], v[8:9], v[124:125], v[18:19]
	v_pk_fma_f32 v[10:11], v[10:11], v[126:127], v[20:21]
	s_mov_b32 s100, 0x3f0000
	v_lshl_add_u64 v[28:29], v[24:25], 0, s[100:101]
	global_load_dwordx2 v[122:123], v[28:29], off
	s_mov_b32 s100, 0x7e00
	v_lshl_add_u64 v[28:29], v[26:27], 0, s[100:101]
	global_load_dwordx4 v[124:127], v[28:29], off
	v_cvt_pk_bf16_f32 v22, v8, v9
	v_cvt_pk_bf16_f32 v23, v10, v11
	s_mov_b32 s100, 0x300000
	v_lshl_add_u64 v[30:31], v[24:25], 0, s[100:101]
	global_store_dwordx2 v[30:31], v[22:23], off
	s_waitcnt vmcnt(46)
	v_lshlrev_b32_e32 v18, 16, v32
	v_and_b32_e32 v19, 0xffff0000, v32
	v_lshlrev_b32_e32 v20, 16, v33
	v_and_b32_e32 v21, 0xffff0000, v33
	v_pk_fma_f32 v[8:9], v[8:9], v[34:35], v[18:19]
	v_pk_fma_f32 v[10:11], v[10:11], v[36:37], v[20:21]
	v_cvt_pk_bf16_f32 v22, v8, v9
	v_cvt_pk_bf16_f32 v23, v10, v11
	s_mov_b32 s100, 0x310000
	v_lshl_add_u64 v[30:31], v[24:25], 0, s[100:101]
	global_store_dwordx2 v[30:31], v[22:23], off
	s_waitcnt vmcnt(44)
	v_lshlrev_b32_e32 v18, 16, v38
	v_and_b32_e32 v19, 0xffff0000, v38
	v_lshlrev_b32_e32 v20, 16, v39
	v_and_b32_e32 v21, 0xffff0000, v39
	v_pk_fma_f32 v[8:9], v[8:9], v[40:41], v[18:19]
	v_pk_fma_f32 v[10:11], v[10:11], v[42:43], v[20:21]
	v_cvt_pk_bf16_f32 v22, v8, v9
	v_cvt_pk_bf16_f32 v23, v10, v11
	s_mov_b32 s100, 0x320000
	v_lshl_add_u64 v[30:31], v[24:25], 0, s[100:101]
	global_store_dwordx2 v[30:31], v[22:23], off
	s_waitcnt vmcnt(42)
	v_lshlrev_b32_e32 v18, 16, v44
	v_and_b32_e32 v19, 0xffff0000, v44
	v_lshlrev_b32_e32 v20, 16, v45
	v_and_b32_e32 v21, 0xffff0000, v45
	v_pk_fma_f32 v[8:9], v[8:9], v[46:47], v[18:19]
	v_pk_fma_f32 v[10:11], v[10:11], v[48:49], v[20:21]
	v_cvt_pk_bf16_f32 v22, v8, v9
	v_cvt_pk_bf16_f32 v23, v10, v11
	s_mov_b32 s100, 0x330000
	v_lshl_add_u64 v[30:31], v[24:25], 0, s[100:101]
	global_store_dwordx2 v[30:31], v[22:23], off
	s_waitcnt vmcnt(40)
; __device__ __forceinline__ unsigned pk2(float lo, float hi) { const f32v2_t v = {lo, hi}; const bf16v2_t b = __builtin_convertvector(v, bf16v2_t); return __builtin_bit_cast(unsigned, b); }
; __device__ __forceinline__ float bflo(unsigned w) { return __uint_as_float(w << 16); }
; __device__ __forceinline__ float bfhi(unsigned w) { return __uint_as_float(w & 0xffff0000u); }
; __device__ __forceinline__ int otid() { int t = threadIdx.x; asm volatile("" : "+v"(t)); return t; }
; __device__ __forceinline__ void gla_scan(const Args& a, int G, size_t dst_off = WS_KV) {
;     ...
;     for (int id = blockIdx.x * 512 + otid(); id < 16 * 256 * 32; id += G * 512) {
;         const int bh = id >> 13, v = (id >> 5) & 255, d0 = (id & 31) * 4;
;         float s0 = 0.f, s1 = 0.f, s2 = 0.f, s3 = 0.f;
; #pragma unroll 8
;         for (int n = 0; n < 64; ++n) {
;             const int unit = bh * 64 + n;
;             u32x2* p = (u32x2*)(KV + ((size_t)unit * 256 + v) * 128 + d0);
;             const u32x2 kv = *p; const f32x4 dc = *(const f32x4*)(DEC + (size_t)unit * 128 + d0);
;             u32x2 o; o.x = pk2(s0, s1); o.y = pk2(s2, s3); *(u32x2*)((char*)p + dd) = o;
;             s0 = dc[0] * s0 + bflo(kv.x); s1 = dc[1] * s1 + bfhi(kv.x); s2 = dc[2] * s2 + bflo(kv.y); s3 = dc[3] * s3 + bfhi(kv.y);
;         }
	v_lshlrev_b32_e32 v18, 16, v50
	v_and_b32_e32 v19, 0xffff0000, v50
	v_lshlrev_b32_e32 v20, 16, v51
	v_and_b32_e32 v21, 0xffff0000, v51
	v_pk_fma_f32 v[8:9], v[8:9], v[52:53], v[18:19]
	v_pk_fma_f32 v[10:11], v[10:11], v[54:55], v[20:21]
	v_cvt_pk_bf16_f32 v22, v8, v9
	v_cvt_pk_bf16_f32 v23, v10, v11
	s_mov_b32 s100, 0x340000
	v_lshl_add_u64 v[30:31], v[24:25], 0, s[100:101]
	global_store_dwordx2 v[30:31], v[22:23], off
	s_waitcnt vmcnt(38)
	v_lshlrev_b32_e32 v18, 16, v56
	v_and_b32_e32 v19, 0xffff0000, v56
	v_lshlrev_b32_e32 v20, 16, v57
	v_and_b32_e32 v21, 0xffff0000, v57
	v_pk_fma_f32 v[8:9], v[8:9], v[58:59], v[18:19]
	v_pk_fma_f32 v[10:11], v[10:11], v[60:61], v[20:21]
	v_cvt_pk_bf16_f32 v22, v8, v9
	v_cvt_pk_bf16_f32 v23, v10, v11
	s_mov_b32 s100, 0x350000
	v_lshl_add_u64 v[30:31], v[24:25], 0, s[100:101]
	global_store_dwordx2 v[30:31], v[22:23], off
	s_waitcnt vmcnt(36)
	v_lshlrev_b32_e32 v18, 16, v62
	v_and_b32_e32 v19, 0xffff0000, v62
	v_lshlrev_b32_e32 v20, 16, v63
	v_and_b32_e32 v21, 0xffff0000, v63
	v_pk_fma_f32 v[8:9], v[8:9], v[64:65], v[18:19]
	v_pk_fma_f32 v[10:11], v[10:11], v[66:67], v[20:21]
	v_cvt_pk_bf16_f32 v22, v8, v9
	v_cvt_pk_bf16_f32 v23, v10, v11
	s_mov_b32 s100, 0x360000
	v_lshl_add_u64 v[30:31], v[24:25], 0, s[100:101]
	global_store_dwordx2 v[30:31], v[22:23], off
	s_waitcnt vmcnt(34)
	v_lshlrev_b32_e32 v18, 16, v68
	v_and_b32_e32 v19, 0xffff0000, v68
	v_lshlrev_b32_e32 v20, 16, v69
	v_and_b32_e32 v21, 0xffff0000, v69
	v_pk_fma_f32 v[8:9], v[8:9], v[70:71], v[18:19]
	v_pk_fma_f32 v[10:11], v[10:11], v[72:73], v[20:21]
	v_cvt_pk_bf16_f32 v22, v8, v9
	v_cvt_pk_bf16_f32 v23, v10, v11
	s_mov_b32 s100, 0x370000
	v_lshl_add_u64 v[30:31], v[24:25], 0, s[100:101]
	global_store_dwordx2 v[30:31], v[22:23], off
	s_waitcnt vmcnt(32)
	v_lshlrev_b32_e32 v18, 16, v74
	v_and_b32_e32 v19, 0xffff0000, v74
	v_lshlrev_b32_e32 v20, 16, v75
	v_and_b32_e32 v21, 0xffff0000, v75
	v_pk_fma_f32 v[8:9], v[8:9], v[76:77], v[18:19]
	v_pk_fma_f32 v[10:11], v[10:11], v[78:79], v[20:21]
	v_cvt_pk_bf16_f32 v22, v8, v9
	v_cvt_pk_bf16_f32 v23, v10, v11
	s_mov_b32 s100, 0x380000
	v_lshl_add_u64 v[30:31], v[24:25], 0, s[100:101]
	global_store_dwordx2 v[30:31], v[22:23], off
	s_waitcnt vmcnt(30)
	v_lshlrev_b32_e32 v18, 16, v80
	v_and_b32_e32 v19, 0xffff0000, v80
	v_lshlrev_b32_e32 v20, 16, v81
	v_and_b32_e32 v21, 0xffff0000, v81
	v_pk_fma_f32 v[8:9], v[8:9], v[82:83], v[18:19]
	v_pk_fma_f32 v[10:11], v[10:11], v[84:85], v[20:21]
	v_cvt_pk_bf16_f32 v22, v8, v9
	v_cvt_pk_bf16_f32 v23, v10, v11
	s_mov_b32 s100, 0x390000
	v_lshl_add_u64 v[30:31], v[24:25], 0, s[100:101]
	global_store_dwordx2 v[30:31], v[22:23], off
	s_waitcnt vmcnt(28)
	v_lshlrev_b32_e32 v18, 16, v86
	v_and_b32_e32 v19, 0xffff0000, v86
	v_lshlrev_b32_e32 v20, 16, v87
	v_and_b32_e32 v21, 0xffff0000, v87
	v_pk_fma_f32 v[8:9], v[8:9], v[88:89], v[18:19]
	v_pk_fma_f32 v[10:11], v[10:11], v[90:91], v[20:21]
	v_cvt_pk_bf16_f32 v22, v8, v9
	v_cvt_pk_bf16_f32 v23, v10, v11
	s_mov_b32 s100, 0x3a0000
	v_lshl_add_u64 v[30:31], v[24:25], 0, s[100:101]
	global_store_dwordx2 v[30:31], v[22:23], off
	s_waitcnt vmcnt(26)
	v_lshlrev_b32_e32 v18, 16, v92
	v_and_b32_e32 v19, 0xffff0000, v92
	v_lshlrev_b32_e32 v20, 16, v93
	v_and_b32_e32 v21, 0xffff0000, v93
	v_pk_fma_f32 v[8:9], v[8:9], v[94:95], v[18:19]
	v_pk_fma_f32 v[10:11], v[10:11], v[96:97], v[20:21]
	v_cvt_pk_bf16_f32 v22, v8, v9
	v_cvt_pk_bf16_f32 v23, v10, v11
	s_mov_b32 s100, 0x3b0000
	v_lshl_add_u64 v[30:31], v[24:25], 0, s[100:101]
	global_store_dwordx2 v[30:31], v[22:23], off
	s_waitcnt vmcnt(24)
	v_lshlrev_b32_e32 v18, 16, v98
	v_and_b32_e32 v19, 0xffff0000, v98
	v_lshlrev_b32_e32 v20, 16, v99
	v_and_b32_e32 v21, 0xffff0000, v99
	v_pk_fma_f32 v[8:9], v[8:9], v[100:101], v[18:19]
	v_pk_fma_f32 v[10:11], v[10:11], v[102:103], v[20:21]
	v_cvt_pk_bf16_f32 v22, v8, v9
	v_cvt_pk_bf16_f32 v23, v10, v11
	s_mov_b32 s100, 0x3c0000
	v_lshl_add_u64 v[30:31], v[24:25], 0, s[100:101]
	global_store_dwordx2 v[30:31], v[22:23], off
	s_waitcnt vmcnt(22)
	v_lshlrev_b32_e32 v18, 16, v104
	v_and_b32_e32 v19, 0xffff0000, v104
	v_lshlrev_b32_e32 v20, 16, v105
	v_and_b32_e32 v21, 0xffff0000, v105
	v_pk_fma_f32 v[8:9], v[8:9], v[106:107], v[18:19]
	v_pk_fma_f32 v[10:11], v[10:11], v[108:109], v[20:21]
	v_cvt_pk_bf16_f32 v22, v8, v9
	v_cvt_pk_bf16_f32 v23, v10, v11
	s_mov_b32 s100, 0x3d0000
	v_lshl_add_u64 v[30:31], v[24:25], 0, s[100:101]
	global_store_dwordx2 v[30:31], v[22:23], off
	s_waitcnt vmcnt(20)
	v_lshlrev_b32_e32 v18, 16, v110
	v_and_b32_e32 v19, 0xffff0000, v110
	v_lshlrev_b32_e32 v20, 16, v111
	v_and_b32_e32 v21, 0xffff0000, v111
	v_pk_fma_f32 v[8:9], v[8:9], v[112:113], v[18:19]
	v_pk_fma_f32 v[10:11], v[10:11], v[114:115], v[20:21]
	v_cvt_pk_bf16_f32 v22, v8, v9
	v_cvt_pk_bf16_f32 v23, v10, v11
	s_mov_b32 s100, 0x3e0000
	v_lshl_add_u64 v[30:31], v[24:25], 0, s[100:101]
	global_store_dwordx2 v[30:31], v[22:23], off
	s_waitcnt vmcnt(18)
	v_lshlrev_b32_e32 v18, 16, v116
	v_and_b32_e32 v19, 0xffff0000, v116
	v_lshlrev_b32_e32 v20, 16, v117
	v_and_b32_e32 v21, 0xffff0000, v117
	v_pk_fma_f32 v[8:9], v[8:9], v[118:119], v[18:19]
	v_pk_fma_f32 v[10:11], v[10:11], v[120:121], v[20:21]
	v_cvt_pk_bf16_f32 v22, v8, v9
	v_cvt_pk_bf16_f32 v23, v10, v11
	s_mov_b32 s100, 0x3f0000
	v_lshl_add_u64 v[30:31], v[24:25], 0, s[100:101]
	global_store_dwordx2 v[30:31], v[22:23], off
	s_waitcnt vmcnt(16)
	v_lshlrev_b32_e32 v18, 16, v122
	v_and_b32_e32 v19, 0xffff0000, v122
	v_lshlrev_b32_e32 v20, 16, v123
	v_and_b32_e32 v21, 0xffff0000, v123
	v_pk_fma_f32 v[8:9], v[8:9], v[124:125], v[18:19]
	v_pk_fma_f32 v[10:11], v[10:11], v[126:127], v[20:21]
	v_add_u32_e32 v0, 0x20000, v12
	v_cmp_lt_i32_e32 vcc, -1, v12
	v_add_u32_e32 v13, 0x80000, v13
	s_or_b64 s[22:23], vcc, s[22:23]
	v_mov_b32_e32 v12, v0
	s_andn2_b64 exec, exec, s[22:23]
	s_cbranch_execnz .LBB0_323
